# attention: ten K-fragment LDS read addresses precomputed once per phase in spare VGPRs (no per-tile v_xor); no alignment pass
# speedup vs baseline: 1.0116x; 1.0116x over previous
.LBB0_877:
	s_or_b64 exec, exec, s[0:1]
	v_lshrrev_b32_e32 v244, 1, v254
	v_and_b32_e32 v244, 0x80, v244
	v_xor_b32_e32 v244, v244, v254
	v_mov_b32_e32 v1, v244
	s_waitcnt lgkmcnt(0)
	s_barrier
	s_cmp_lg_u32 0, -1
	v_lshrrev_b32_e32 v5, 2, v1
	v_lshrrev_b32_e32 v2, 5, v1
	v_lshlrev_b32_e32 v4, 2, v1
	v_and_b32_e32 v6, 2, v5
	v_and_or_b32 v4, v4, 12, v6
	v_xor_b32_e32 v6, v2, v5
	v_and_or_b32 v4, v6, 1, v4
	v_lshrrev_b32_e32 v6, 1, v1
	v_and_b32_e32 v0, 31, v1
	v_xor_b32_e32 v2, v2, v6
	v_lshlrev_b32_e32 v7, 7, v0
	v_lshlrev_b32_e32 v2, 4, v2
	v_lshlrev_b32_e32 v6, 3, v1
	v_bfe_u32 v3, v1, 5, 1
	v_and_or_b32 v2, v2, 16, v7
	v_and_b32_e32 v7, 0x60, v6
	v_bfe_u32 v8, v1, 2, 2
	v_and_b32_e32 v6, 8, v6
	s_cselect_b32 s0, 0, 0
	v_lshrrev_b32_e32 v9, 3, v1
	v_lshlrev_b32_e32 v12, 10, v3
	v_lshlrev_b32_e32 v13, 8, v8
	v_add_u32_e32 v6, s0, v6
	v_and_b32_e32 v10, 2, v9
	v_bfe_u32 v11, v1, 1, 1
	v_add3_u32 v6, v6, v12, v13
	v_or_b32_e32 v13, 2, v3
	v_lshlrev_b32_e32 v0, 8, v0
	v_bitop3_b32 v12, v10, v3, v11 bitop3:0x36
	v_bitop3_b32 v10, v10, v13, v11 bitop3:0x36
	v_lshl_or_b32 v198, v4, 4, v0
	v_lshlrev_b32_e32 v0, 4, v1
	v_lshlrev_b32_e32 v10, 4, v10
	s_movk_i32 s0, 0x800
	v_lshlrev_b32_e32 v8, 6, v8
	s_movk_i32 s16, 0x4000
	v_and_b32_e32 v0, 0x1f0, v0
	v_lshl_add_u32 v12, v12, 4, v6
	v_add3_u32 v6, v6, v10, s0
	v_xor_b32_e32 v10, 64, v8
	v_or3_b32 v199, v2, v7, s16
	v_lshl_or_b32 v2, v3, 9, v0
	v_mov_b32_e32 v0, 0
	v_add_u32_e32 v188, v12, v8
	v_add_u32_e32 v189, v6, v8
	v_add_u32_e32 v192, v12, v10
	v_add_u32_e32 v193, v6, v10
	v_xor_b32_e32 v10, 0x80, v8
	v_xor_b32_e32 v8, 0xc0, v8
	v_mov_b32_e32 v3, v0
	v_add_u32_e32 v196, v12, v8
	v_add_u32_e32 v197, v6, v8
	v_lshl_add_u64 v[162:163], s[36:37], 0, v[2:3]
	v_and_b32_e32 v2, 15, v1
	v_and_b32_e32 v5, 12, v5
	v_bfe_u32 v8, v1, 6, 2
	v_bitop3_b32 v2, v5, v2, v8 bitop3:0x36
	s_not_b32 s0, s2
	v_add_u32_e32 v3, 0x200, v1
	v_lshrrev_b32_e32 v4, 4, v1
	v_lshlrev_b32_e32 v2, 4, v2
	s_movk_i32 s7, 0x180
	s_add_i32 s17, s30, s0
	v_mad_u64_u32 v[164:165], s[0:1], v4, s7, v[2:3]
	v_bfe_u32 v7, v1, 4, 5
	v_lshrrev_b32_e32 v5, 4, v3
	s_mov_b32 s0, 0x1ffffe0
	v_add_u32_e32 v195, v6, v10
	s_movk_i32 s6, 0xc0
	v_ashrrev_i32_e32 v6, 6, v1
	v_ashrrev_i32_e32 v200, 8, v1
	v_and_or_b32 v5, v5, s0, v7
	v_xor_b32_e32 v1, v4, v1
	v_mad_u64_u32 v[166:167], s[0:1], v5, s7, v[2:3]
	v_mul_lo_u32 v5, v9, s6
	v_lshlrev_b32_e32 v1, 3, v1
	v_and_or_b32 v1, v1, 56, v5
	v_mov_b32_e32 v5, 0x100
	v_lshlrev_b32_e32 v4, 10, v6
	v_lshl_add_u32 v168, v1, 1, v5
	v_lshrrev_b32_e32 v1, 9, v3
	v_mul_u32_u24_e32 v1, 0x3000, v1
	v_mul_u32_u24_e32 v3, 0x180, v7
	v_add_u32_e32 v203, 0, v4
	s_mov_b32 s3, 0
	v_add_u32_e32 v194, v12, v10
	v_and_b32_e32 v201, 3, v6
	v_mov_b32_e32 v165, v0
	v_mov_b32_e32 v167, v0
	v_mov_b32_e32 v169, v0
	s_movk_i32 s36, 0x3000
	v_add3_u32 v170, v1, v3, v2
	s_movk_i32 s37, 0x1000
	s_movk_i32 s40, 0x2000
	v_add_u32_e32 v204, 0x2000, v203
	v_add_u32_e32 v205, 0x4000, v203
	s_mov_b64 s[0:1], 0x1dc06000
	s_mov_b32 s41, 0x8000
	s_mov_b64 s[6:7], 0x1dc0c000
	s_movk_i32 s44, 0xfe0
	s_movk_i32 s45, 0x2200
	s_mov_b32 s50, 0xc000
	s_mov_b32 s51, 0x10000
	s_mov_b32 s52, 0x14000
	s_mov_b32 s53, 0x18000
	v_mbcnt_hi_u32_b32 v191, -1, v186
	v_readfirstlane_b32 s74, v203
	v_readfirstlane_b32 s76, v244
	s_nop 0
	s_bfe_u32 s76, s76, 0x10007
	v_xor_b32_e32 v171, 0x20, v198
	v_xor_b32_e32 v174, 0x40, v198
	v_xor_b32_e32 v175, 0x60, v198
	v_xor_b32_e32 v176, 0x80, v198
	v_xor_b32_e32 v177, 0xa0, v198
	v_xor_b32_e32 v178, 0xc0, v198
	v_xor_b32_e32 v179, 0xe0, v198
	v_xor_b32_e32 v202, 0x20, v199
	v_xor_b32_e32 v207, 0x40, v199
	v_xor_b32_e32 v208, 0x60, v199
	s_mov_b32 s54, 0
	s_branch .LBB0_879

.LBB0_884:
	s_add_u32 s72, s8, s0
	s_addc_u32 s73, s9, s1
	s_add_u32 m0, s74, 0x6000
	s_nop 0
	global_load_lds_dwordx4 v164, s[72:73]
	s_add_u32 m0, s74, 0x8000
	s_nop 0
	global_load_lds_dwordx4 v170, s[72:73]
	s_add_u32 m0, s74, 0xa000
	s_nop 0
	global_load_lds_dwordx4 v168, s[72:73]
	s_cmp_gt_u32 s57, s75
	s_cbranch_scc1 .LBB0_888
	ds_read_b128 v[146:149], v198
	ds_read_b128 v[150:153], v198 offset:8192
	ds_read_b128 v[246:249], v171
	ds_read_b128 v[250:253], v171 offset:8192
	ds_read_b128 v[180:183], v174
	ds_read_b128 v[184:187], v174 offset:8192
	s_waitcnt lgkmcnt(4)
	v_mfma_f32_32x32x16_bf16 v[82:97], v[146:149], v[98:101], v[210:225]
	v_mfma_f32_32x32x16_bf16 v[66:81], v[150:153], v[98:101], v[210:225]
	ds_read_b128 v[146:149], v175
	ds_read_b128 v[150:153], v175 offset:8192
	s_waitcnt lgkmcnt(4)
	v_mfma_f32_32x32x16_bf16 v[82:97], v[246:249], v[102:105], v[82:97]
	v_mfma_f32_32x32x16_bf16 v[66:81], v[250:253], v[102:105], v[66:81]
	ds_read_b128 v[246:249], v176
	ds_read_b128 v[250:253], v176 offset:8192
	s_waitcnt lgkmcnt(4)
	v_mfma_f32_32x32x16_bf16 v[82:97], v[180:183], v[106:109], v[82:97]
	v_mfma_f32_32x32x16_bf16 v[66:81], v[184:187], v[106:109], v[66:81]
	ds_read_b128 v[180:183], v177
	ds_read_b128 v[184:187], v177 offset:8192
	s_waitcnt lgkmcnt(4)
	v_mfma_f32_32x32x16_bf16 v[82:97], v[146:149], v[110:113], v[82:97]
	v_mfma_f32_32x32x16_bf16 v[66:81], v[150:153], v[110:113], v[66:81]
	ds_read_b128 v[146:149], v178
	ds_read_b128 v[150:153], v178 offset:8192
	s_waitcnt lgkmcnt(4)
	v_mfma_f32_32x32x16_bf16 v[82:97], v[246:249], v[122:125], v[82:97]
	v_mfma_f32_32x32x16_bf16 v[66:81], v[250:253], v[122:125], v[66:81]
	ds_read_b128 v[246:249], v179
	ds_read_b128 v[250:253], v179 offset:8192
	s_waitcnt lgkmcnt(4)
	v_mfma_f32_32x32x16_bf16 v[82:97], v[180:183], v[114:117], v[82:97]
	v_mfma_f32_32x32x16_bf16 v[66:81], v[184:187], v[114:117], v[66:81]
	ds_read_b128 v[180:183], v199
	ds_read_b128 v[184:187], v199 offset:4096
	s_waitcnt lgkmcnt(4)
	v_mfma_f32_32x32x16_bf16 v[82:97], v[146:149], v[118:121], v[82:97]
	v_mfma_f32_32x32x16_bf16 v[66:81], v[150:153], v[118:121], v[66:81]
	ds_read_b128 v[146:149], v202
	ds_read_b128 v[150:153], v202 offset:4096
	s_waitcnt lgkmcnt(4)
	v_mfma_f32_32x32x16_bf16 v[82:97], v[246:249], v[126:129], v[82:97]
	v_mfma_f32_32x32x16_bf16 v[66:81], v[250:253], v[126:129], v[66:81]
	ds_read_b128 v[246:249], v207
	ds_read_b128 v[250:253], v207 offset:4096
	s_waitcnt lgkmcnt(4)
	v_mfma_f32_32x32x16_bf16 v[82:97], v[180:183], v[130:133], v[82:97]
	v_mfma_f32_32x32x16_bf16 v[66:81], v[184:187], v[130:133], v[66:81]
	ds_read_b128 v[180:183], v208
	ds_read_b128 v[184:187], v208 offset:4096
	s_waitcnt lgkmcnt(4)
	v_mfma_f32_32x32x16_bf16 v[82:97], v[146:149], v[134:137], v[82:97]
	v_mfma_f32_32x32x16_bf16 v[66:81], v[150:153], v[134:137], v[66:81]
	s_waitcnt lgkmcnt(2)
	v_mfma_f32_32x32x16_bf16 v[82:97], v[246:249], v[138:141], v[82:97]
	v_mfma_f32_32x32x16_bf16 v[66:81], v[250:253], v[138:141], v[66:81]
	s_waitcnt lgkmcnt(0)
	v_mfma_f32_32x32x16_bf16 v[66:81], v[184:187], v[142:145], v[66:81]
	v_mfma_f32_32x32x16_bf16 v[82:97], v[180:183], v[142:145], v[82:97]
	ds_read_b64_tr_b16 v[158:159], v188 offset:0
	ds_read_b64_tr_b16 v[160:161], v189 offset:0
	ds_read_b64_tr_b16 v[154:155], v192 offset:0
	ds_read_b64_tr_b16 v[156:157], v193 offset:0
	ds_read_b64_tr_b16 v[150:151], v194 offset:0
	ds_read_b64_tr_b16 v[152:153], v195 offset:0
	ds_read_b64_tr_b16 v[146:147], v196 offset:0
	ds_read_b64_tr_b16 v[148:149], v197 offset:0
	s_nop 2
	v_max3_f32 v1, v66, v67, v68
	v_max3_f32 v180, v69, v70, v71
	v_max3_f32 v1, v1, v72, v73
	v_max3_f32 v180, v180, v74, v75
	v_max3_f32 v1, v1, v76, v77
	v_max3_f32 v180, v180, v78, v79
	v_max3_f32 v1, v1, v80, v81
	v_max3_f32 v181, v82, v83, v84
	v_max3_f32 v182, v85, v86, v87
	v_max3_f32 v181, v181, v88, v89
	v_max3_f32 v182, v182, v90, v91
	v_max3_f32 v181, v181, v92, v93
	v_max3_f32 v182, v182, v94, v95
	v_max3_f32 v181, v181, v96, v97
	v_max3_f32 v1, v1, v180, v181
	v_max_f32_e32 v1, v1, v182
	s_cmp_eq_u32 s57, 0
	s_cbranch_scc1 .Latt_rare0
	v_cmp_lt_f32_e32 vcc, 0x41000000, v1
	s_cbranch_vccz .Latt_common0

.LBB0_890:
	s_cmp_ge_u32 s57, s75
	s_cbranch_scc1 .LBB0_883
	ds_read_b128 v[146:149], v198 offset:24576
	ds_read_b128 v[150:153], v198 offset:32768
	ds_read_b128 v[246:249], v171 offset:24576
	ds_read_b128 v[250:253], v171 offset:32768
	ds_read_b128 v[180:183], v174 offset:24576
	ds_read_b128 v[184:187], v174 offset:32768
	s_waitcnt lgkmcnt(4)
	v_mfma_f32_32x32x16_bf16 v[82:97], v[146:149], v[98:101], v[210:225]
	v_mfma_f32_32x32x16_bf16 v[66:81], v[150:153], v[98:101], v[210:225]
	ds_read_b128 v[146:149], v175 offset:24576
	ds_read_b128 v[150:153], v175 offset:32768
	s_waitcnt lgkmcnt(4)
	v_mfma_f32_32x32x16_bf16 v[82:97], v[246:249], v[102:105], v[82:97]
	v_mfma_f32_32x32x16_bf16 v[66:81], v[250:253], v[102:105], v[66:81]
	ds_read_b128 v[246:249], v176 offset:24576
	ds_read_b128 v[250:253], v176 offset:32768
	s_waitcnt lgkmcnt(4)
	v_mfma_f32_32x32x16_bf16 v[82:97], v[180:183], v[106:109], v[82:97]
	v_mfma_f32_32x32x16_bf16 v[66:81], v[184:187], v[106:109], v[66:81]
	ds_read_b128 v[180:183], v177 offset:24576
	ds_read_b128 v[184:187], v177 offset:32768
	s_waitcnt lgkmcnt(4)
	v_mfma_f32_32x32x16_bf16 v[82:97], v[146:149], v[110:113], v[82:97]
	v_mfma_f32_32x32x16_bf16 v[66:81], v[150:153], v[110:113], v[66:81]
	ds_read_b128 v[146:149], v178 offset:24576
	ds_read_b128 v[150:153], v178 offset:32768
	s_waitcnt lgkmcnt(4)
	v_mfma_f32_32x32x16_bf16 v[82:97], v[246:249], v[122:125], v[82:97]
	v_mfma_f32_32x32x16_bf16 v[66:81], v[250:253], v[122:125], v[66:81]
	ds_read_b128 v[246:249], v179 offset:24576
	ds_read_b128 v[250:253], v179 offset:32768
	s_waitcnt lgkmcnt(4)
	v_mfma_f32_32x32x16_bf16 v[82:97], v[180:183], v[114:117], v[82:97]
	v_mfma_f32_32x32x16_bf16 v[66:81], v[184:187], v[114:117], v[66:81]
	ds_read_b128 v[180:183], v199 offset:24576
	ds_read_b128 v[184:187], v199 offset:28672
	s_waitcnt lgkmcnt(4)
	v_mfma_f32_32x32x16_bf16 v[82:97], v[146:149], v[118:121], v[82:97]
	v_mfma_f32_32x32x16_bf16 v[66:81], v[150:153], v[118:121], v[66:81]
	ds_read_b128 v[146:149], v202 offset:24576
	ds_read_b128 v[150:153], v202 offset:28672
	s_waitcnt lgkmcnt(4)
	v_mfma_f32_32x32x16_bf16 v[82:97], v[246:249], v[126:129], v[82:97]
	v_mfma_f32_32x32x16_bf16 v[66:81], v[250:253], v[126:129], v[66:81]
	ds_read_b128 v[246:249], v207 offset:24576
	ds_read_b128 v[250:253], v207 offset:28672
	s_waitcnt lgkmcnt(4)
	v_mfma_f32_32x32x16_bf16 v[82:97], v[180:183], v[130:133], v[82:97]
	v_mfma_f32_32x32x16_bf16 v[66:81], v[184:187], v[130:133], v[66:81]
	ds_read_b128 v[180:183], v208 offset:24576
	ds_read_b128 v[184:187], v208 offset:28672
	s_waitcnt lgkmcnt(4)
	v_mfma_f32_32x32x16_bf16 v[82:97], v[146:149], v[134:137], v[82:97]
	v_mfma_f32_32x32x16_bf16 v[66:81], v[150:153], v[134:137], v[66:81]
	s_waitcnt lgkmcnt(2)
	v_mfma_f32_32x32x16_bf16 v[82:97], v[246:249], v[138:141], v[82:97]
	v_mfma_f32_32x32x16_bf16 v[66:81], v[250:253], v[138:141], v[66:81]
	s_waitcnt lgkmcnt(0)
	v_mfma_f32_32x32x16_bf16 v[66:81], v[184:187], v[142:145], v[66:81]
	v_mfma_f32_32x32x16_bf16 v[82:97], v[180:183], v[142:145], v[82:97]
	ds_read_b64_tr_b16 v[158:159], v188 offset:0x6000
	ds_read_b64_tr_b16 v[160:161], v189 offset:0x6000
	ds_read_b64_tr_b16 v[154:155], v192 offset:0x6000
	ds_read_b64_tr_b16 v[156:157], v193 offset:0x6000
	ds_read_b64_tr_b16 v[150:151], v194 offset:0x6000
	ds_read_b64_tr_b16 v[152:153], v195 offset:0x6000
	ds_read_b64_tr_b16 v[146:147], v196 offset:0x6000
	ds_read_b64_tr_b16 v[148:149], v197 offset:0x6000
	s_nop 2
	v_max3_f32 v1, v66, v67, v68
	v_max3_f32 v180, v69, v70, v71
	v_max3_f32 v1, v1, v72, v73
	v_max3_f32 v180, v180, v74, v75
	v_max3_f32 v1, v1, v76, v77
	v_max3_f32 v180, v180, v78, v79
	v_max3_f32 v1, v1, v80, v81
	v_max3_f32 v181, v82, v83, v84
	v_max3_f32 v182, v85, v86, v87
	v_max3_f32 v181, v181, v88, v89
	v_max3_f32 v182, v182, v90, v91
	v_max3_f32 v181, v181, v92, v93
	v_max3_f32 v182, v182, v94, v95
	v_max3_f32 v181, v181, v96, v97
	v_max3_f32 v1, v1, v180, v181
	v_max_f32_e32 v1, v1, v182
	v_cmp_lt_f32_e32 vcc, 0x41000000, v1
	s_cbranch_vccz .Latt_common1
